# MLA attention step blocks rewritten: 6-deep LDS fragment ring (prefetch K/V frags), in-place exp, evenly interleaved VALU
# speedup vs baseline: 1.0003x; 1.0003x over previous
; #define LAS __attribute__((address_space(3)))
; DI unsigned cvt_pk(float lo, float hi) { unsigned r; asm volatile("v_cvt_pk_bf16_f32 %0, %1, %2" : "=v"(r) : "v"(lo), "v"(hi)); return r; }
; DI float fexp2(float x) { return __builtin_amdgcn_exp2f(x); }
; template <int DK, int DV, int MODE> ...
;     ...
;   auto part2 = [&](f32x16 (&st)[2], int t) __attribute__((always_inline)) {
;     float ps0 = 0.f, ps1 = 0.f, ps2 = 0.f, ps3 = 0.f;
; #pragma unroll
;     for (int kb = 0; kb < 2; ++kb)
; #pragma unroll
;       for (int i = 0; i < 16; i += 4) {
;         const float p0 = fexp2(st[kb][i]), p1 = fexp2(st[kb][i + 1]), p2 = fexp2(st[kb][i + 2]), p3 = fexp2(st[kb][i + 3]);
;         st[kb][i] = p0; st[kb][i + 1] = p1; st[kb][i + 2] = p2; st[kb][i + 3] = p3; ps0 += p0; ps1 += p1; ps2 += p2; ps3 += p3;
;       }
;     lsum += (ps0 + ps1) + (ps2 + ps3);
;     bf16x8 pf[2][2];
; #pragma unroll
;     for (int kb = 0; kb < 2; ++kb)
; #pragma unroll
;       for (int s = 0; s < 2; ++s) { u32x4 pp; pp.x = cvt_pk(st[kb][8 * s], st[kb][8 * s + 1]); pp.y = cvt_pk(st[kb][8 * s + 2], st[kb][8 * s + 3]); pp.z = cvt_pk(st[kb][8 * s + 4], st[kb][8 * s + 5]); pp.w = cvt_pk(st[kb][8 * s + 6], st[kb][8 * s + 7]); pf[kb][s] = __builtin_bit_cast(bf16x8, pp); }
; #pragma unroll
;     for (int db = 0; db < DV / 32; ++db)
; #pragma unroll
;       for (int kb = 0; kb < 2; ++kb)
; #pragma unroll
;         for (int s = 0; s < 2; ++s) {
;           if (MODE == 1 && ((kb == 1 && s == 1 && cwu == 0) || (kb == 0 && s == 0 && cwu != 0))) continue;
;           const bf16x8 vf = *(const LAS bf16x8*)(lds + ATT_VB + (t & 3) * VBUF + (32 * db + r) * VSTR + (2 * kb + s) * 32 + hh * 16);
;           O[db] = __builtin_amdgcn_mfma_f32_32x32x16_bf16(vf, pf[kb][s], O[db], 0, 0, 0);
;         }
;   };
.LBB0_249:
	s_setprio 1
	s_and_b32 s22, s20, 2
	s_mulk_i32 s22, 0x3400
	s_mulk_i32 s21, 0x2400
	v_add_u32_e32 v252, s22, v160
	ds_read_b128 v[196:199], v252
	ds_read_b128 v[200:203], v252 offset:32
	ds_read_b128 v[216:219], v252 offset:64
	ds_read_b128 v[230:233], v252 offset:96
	ds_read_b128 v[234:237], v252 offset:128
	ds_read_b128 v[244:247], v252 offset:160
	v_add_u32_e32 v243, s21, v163
	v_add_u32_e32 v0, 0x80, v167
	v_cmp_gt_i32_e32 vcc, s78, v0
	v_exp_f32_e32 v82, v82
	v_exp_f32_e32 v83, v83
	v_cndmask_b32_e32 v34, 0, v158, vcc
	v_cmp_lt_i32_e32 vcc, s77, v0
	v_exp_f32_e32 v84, v84
	v_exp_f32_e32 v85, v85
	v_cndmask_b32_e32 v0, v34, v159, vcc
	v_cmp_neq_f32_e32 vcc, s53, v143
	v_exp_f32_e32 v86, v86
	v_exp_f32_e32 v87, v87
	v_cndmask_b32_e32 v142, 0, v143, vcc
	v_sub_f32_e32 v34, v0, v142
	v_mov_b32_e32 v35, v34
	v_mov_b32_e32 v36, v34
	v_mov_b32_e32 v37, v34
	v_mov_b32_e32 v38, v34
	v_mov_b32_e32 v39, v34
	v_mov_b32_e32 v40, v34
	v_mov_b32_e32 v41, v34
	v_mov_b32_e32 v42, v34
	v_mov_b32_e32 v43, v34
	v_mov_b32_e32 v44, v34
	v_mov_b32_e32 v45, v34
	v_mov_b32_e32 v46, v34
	v_mov_b32_e32 v47, v34
	v_mov_b32_e32 v48, v34
	v_mov_b32_e32 v49, v34
	v_exp_f32_e32 v88, v88
	v_exp_f32_e32 v89, v89
	s_waitcnt lgkmcnt(5)
	v_mfma_f32_32x32x16_bf16 v[50:65], v[196:199], v[98:101], v[34:49]
	ds_read_b128 v[196:199], v252 offset:6656
	v_exp_f32_e32 v90, v90
	v_exp_f32_e32 v91, v91
	v_exp_f32_e32 v92, v92
	s_waitcnt lgkmcnt(5)
	v_mfma_f32_32x32x16_bf16 v[50:65], v[200:203], v[102:105], v[50:65]
	ds_read_b128 v[200:203], v252 offset:6688
	v_exp_f32_e32 v93, v93
	v_exp_f32_e32 v94, v94
	v_exp_f32_e32 v95, v95
	s_waitcnt lgkmcnt(5)
	v_mfma_f32_32x32x16_bf16 v[50:65], v[216:219], v[106:109], v[50:65]
	ds_read_b128 v[216:219], v252 offset:6720
	v_exp_f32_e32 v96, v96
	v_exp_f32_e32 v97, v97
	v_exp_f32_e32 v66, v66
	s_waitcnt lgkmcnt(5)
	v_mfma_f32_32x32x16_bf16 v[50:65], v[230:233], v[110:113], v[50:65]
	ds_read_b128 v[230:233], v252 offset:6752
	v_exp_f32_e32 v67, v67
	v_cvt_pk_bf16_f32 v168, v82, v83
	v_exp_f32_e32 v68, v68
	v_exp_f32_e32 v69, v69
	s_waitcnt lgkmcnt(5)
	v_mfma_f32_32x32x16_bf16 v[50:65], v[234:237], v[114:117], v[50:65]
	ds_read_b128 v[234:237], v252 offset:6784
	v_cvt_pk_bf16_f32 v169, v84, v85
	v_exp_f32_e32 v70, v70
	v_exp_f32_e32 v71, v71
	v_cvt_pk_bf16_f32 v170, v86, v87
	s_waitcnt lgkmcnt(5)
	v_mfma_f32_32x32x16_bf16 v[50:65], v[244:247], v[118:121], v[50:65]
	ds_read_b128 v[244:247], v252 offset:6816
	v_exp_f32_e32 v72, v72
	v_exp_f32_e32 v73, v73
	v_cvt_pk_bf16_f32 v171, v88, v89
	v_exp_f32_e32 v74, v74
	s_waitcnt lgkmcnt(5)
	v_mfma_f32_32x32x16_bf16 v[34:49], v[196:199], v[98:101], v[34:49]
	ds_read_b128 v[196:199], v243 offset:53248
	v_exp_f32_e32 v75, v75
	v_cvt_pk_bf16_f32 v180, v90, v91
	v_exp_f32_e32 v76, v76
	v_exp_f32_e32 v77, v77
	s_waitcnt lgkmcnt(5)
	v_mfma_f32_32x32x16_bf16 v[34:49], v[200:203], v[102:105], v[34:49]
	ds_read_b128 v[200:203], v243 offset:57856
	v_cvt_pk_bf16_f32 v181, v92, v93
	v_exp_f32_e32 v78, v78
	v_exp_f32_e32 v79, v79
	v_cvt_pk_bf16_f32 v182, v94, v95
	s_waitcnt lgkmcnt(5)
	v_mfma_f32_32x32x16_bf16 v[34:49], v[216:219], v[106:109], v[34:49]
	ds_read_b128 v[216:219], v243 offset:53280
	v_exp_f32_e32 v80, v80
	v_exp_f32_e32 v81, v81
	v_cvt_pk_bf16_f32 v183, v96, v97
	v_add_f32_e32 v172, v82, v86
	s_waitcnt lgkmcnt(5)
	v_mfma_f32_32x32x16_bf16 v[34:49], v[230:233], v[110:113], v[34:49]
	ds_read_b128 v[230:233], v243 offset:57888
	v_add_f32_e32 v173, v83, v87
	v_add_f32_e32 v176, v84, v88
	v_add_f32_e32 v179, v85, v89
	v_add_f32_e32 v172, v90, v172
	v_add_f32_e32 v173, v91, v173
	v_add_f32_e32 v176, v92, v176
	s_waitcnt lgkmcnt(5)
	v_mfma_f32_32x32x16_bf16 v[34:49], v[234:237], v[114:117], v[34:49]
	ds_read_b128 v[234:237], v243 offset:53312
	v_add_f32_e32 v179, v93, v179
	v_add_f32_e32 v172, v94, v172
	v_add_f32_e32 v173, v95, v173
	v_add_f32_e32 v176, v96, v176
	v_add_f32_e32 v179, v97, v179
	v_cvt_pk_bf16_f32 v184, v66, v67
	s_waitcnt lgkmcnt(5)
	v_mfma_f32_32x32x16_bf16 v[34:49], v[244:247], v[118:121], v[34:49]
	ds_read_b128 v[244:247], v243 offset:57920
	v_cvt_pk_bf16_f32 v185, v68, v69
	v_cvt_pk_bf16_f32 v186, v70, v71
	v_cvt_pk_bf16_f32 v187, v72, v73
	v_cvt_pk_bf16_f32 v188, v74, v75
	v_cvt_pk_bf16_f32 v189, v76, v77
	v_cvt_pk_bf16_f32 v190, v78, v79
	s_waitcnt lgkmcnt(5)
	v_mfma_f32_32x32x16_bf16 v[18:33], v[196:199], v[168:171], v[18:33]
	ds_read_b128 v[196:199], v243 offset:53344
	v_cvt_pk_bf16_f32 v191, v80, v81
	v_add_f32_e32 v172, v66, v172
	v_add_f32_e32 v173, v67, v173
	v_add_f32_e32 v176, v68, v176
	v_add_f32_e32 v179, v69, v179
	v_add_f32_e32 v172, v70, v172
	s_waitcnt lgkmcnt(5)
	v_mfma_f32_32x32x16_bf16 v[2:17], v[200:203], v[168:171], v[2:17]
	ds_read_b128 v[200:203], v243 offset:57952
	v_add_f32_e32 v173, v71, v173
	v_add_f32_e32 v176, v72, v176
	v_add_f32_e32 v179, v73, v179
	v_add_f32_e32 v172, v74, v172
	v_add_f32_e32 v173, v75, v173
	v_add_f32_e32 v176, v76, v176
	s_waitcnt lgkmcnt(5)
	v_mfma_f32_32x32x16_bf16 v[18:33], v[216:219], v[180:183], v[18:33]
	v_add_f32_e32 v179, v77, v179
	v_add_f32_e32 v172, v78, v172
	v_add_f32_e32 v173, v79, v173
	v_add_f32_e32 v176, v80, v176
	v_add_f32_e32 v179, v81, v179
	v_add_f32_e32 v172, v172, v173
	s_waitcnt lgkmcnt(4)
	v_mfma_f32_32x32x16_bf16 v[2:17], v[230:233], v[180:183], v[2:17]
	v_add_f32_e32 v176, v176, v179
	s_waitcnt lgkmcnt(3)
	v_mfma_f32_32x32x16_bf16 v[18:33], v[234:237], v[184:187], v[18:33]
	s_waitcnt lgkmcnt(2)
	v_mfma_f32_32x32x16_bf16 v[2:17], v[244:247], v[184:187], v[2:17]
	s_waitcnt lgkmcnt(1)
	v_mfma_f32_32x32x16_bf16 v[18:33], v[196:199], v[188:191], v[18:33]
	s_waitcnt lgkmcnt(0)
	v_mfma_f32_32x32x16_bf16 v[2:17], v[200:203], v[188:191], v[2:17]
	v_add_f32_e32 v0, v172, v176
	v_add_f32_e32 v161, v161, v0
	s_setprio 0
	s_waitcnt lgkmcnt(0)
	s_barrier

; #define LAS __attribute__((address_space(3)))
; DI unsigned cvt_pk(float lo, float hi) { unsigned r; asm volatile("v_cvt_pk_bf16_f32 %0, %1, %2" : "=v"(r) : "v"(lo), "v"(hi)); return r; }
; DI float fexp2(float x) { return __builtin_amdgcn_exp2f(x); }
; template <int DK, int DV, int MODE> ...
;     ...
;   auto part2 = [&](f32x16 (&st)[2], int t) __attribute__((always_inline)) {
;     float ps0 = 0.f, ps1 = 0.f, ps2 = 0.f, ps3 = 0.f;
; #pragma unroll
;     for (int kb = 0; kb < 2; ++kb)
; #pragma unroll
;       for (int i = 0; i < 16; i += 4) {
;         const float p0 = fexp2(st[kb][i]), p1 = fexp2(st[kb][i + 1]), p2 = fexp2(st[kb][i + 2]), p3 = fexp2(st[kb][i + 3]);
;         st[kb][i] = p0; st[kb][i + 1] = p1; st[kb][i + 2] = p2; st[kb][i + 3] = p3; ps0 += p0; ps1 += p1; ps2 += p2; ps3 += p3;
;       }
;     lsum += (ps0 + ps1) + (ps2 + ps3);
;     bf16x8 pf[2][2];
; #pragma unroll
;     for (int kb = 0; kb < 2; ++kb)
; #pragma unroll
;       for (int s = 0; s < 2; ++s) { u32x4 pp; pp.x = cvt_pk(st[kb][8 * s], st[kb][8 * s + 1]); pp.y = cvt_pk(st[kb][8 * s + 2], st[kb][8 * s + 3]); pp.z = cvt_pk(st[kb][8 * s + 4], st[kb][8 * s + 5]); pp.w = cvt_pk(st[kb][8 * s + 6], st[kb][8 * s + 7]); pf[kb][s] = __builtin_bit_cast(bf16x8, pp); }
; #pragma unroll
;     for (int db = 0; db < DV / 32; ++db)
; #pragma unroll
;       for (int kb = 0; kb < 2; ++kb)
; #pragma unroll
;         for (int s = 0; s < 2; ++s) {
;           if (MODE == 1 && ((kb == 1 && s == 1 && cwu == 0) || (kb == 0 && s == 0 && cwu != 0))) continue;
;           const bf16x8 vf = *(const LAS bf16x8*)(lds + ATT_VB + (t & 3) * VBUF + (32 * db + r) * VSTR + (2 * kb + s) * 32 + hh * 16);
;           O[db] = __builtin_amdgcn_mfma_f32_32x32x16_bf16(vf, pf[kb][s], O[db], 0, 0, 0);
;         }
;   };
.LBB0_273:
	s_setprio 1
	s_add_i32 s25, s19, -4
	s_and_b32 s21, s25, 3
	s_mul_i32 s26, s21, 0x3400
	s_and_b32 s23, s23, 2
	v_add_u32_e32 v252, s26, v160
	s_mul_i32 s26, s23, 0x2400
	ds_read_b128 v[196:199], v252
	ds_read_b128 v[200:203], v252 offset:32
	ds_read_b128 v[216:219], v252 offset:64
	ds_read_b128 v[230:233], v252 offset:96
	ds_read_b128 v[234:237], v252 offset:128
	ds_read_b128 v[244:247], v252 offset:160
	v_add_u32_e32 v243, s26, v163
	v_add_u32_e32 v0, 64, v167
	v_cmp_gt_i32_e32 vcc, s78, v0
	v_exp_f32_e32 v50, v50
	v_exp_f32_e32 v51, v51
	v_cndmask_b32_e32 v66, 0, v158, vcc
	v_cmp_lt_i32_e32 vcc, s77, v0
	v_exp_f32_e32 v52, v52
	v_exp_f32_e32 v53, v53
	v_cndmask_b32_e32 v0, v66, v159, vcc
	v_cmp_neq_f32_e32 vcc, s53, v143
	v_exp_f32_e32 v54, v54
	v_exp_f32_e32 v55, v55
	v_cndmask_b32_e32 v144, 0, v143, vcc
	v_sub_f32_e32 v66, v0, v144
	v_mov_b32_e32 v67, v66
	v_mov_b32_e32 v68, v66
	v_mov_b32_e32 v69, v66
	v_mov_b32_e32 v70, v66
	v_mov_b32_e32 v71, v66
	v_mov_b32_e32 v72, v66
	v_mov_b32_e32 v73, v66
	v_mov_b32_e32 v74, v66
	v_mov_b32_e32 v75, v66
	v_mov_b32_e32 v76, v66
	v_mov_b32_e32 v77, v66
	v_mov_b32_e32 v78, v66
	v_mov_b32_e32 v79, v66
	v_mov_b32_e32 v80, v66
	v_mov_b32_e32 v81, v66
	v_exp_f32_e32 v56, v56
	v_exp_f32_e32 v57, v57
	s_waitcnt lgkmcnt(5)
	v_mfma_f32_32x32x16_bf16 v[82:97], v[196:199], v[98:101], v[66:81]
	ds_read_b128 v[196:199], v252 offset:6656
	v_exp_f32_e32 v58, v58
	v_exp_f32_e32 v59, v59
	v_exp_f32_e32 v60, v60
	s_waitcnt lgkmcnt(5)
	v_mfma_f32_32x32x16_bf16 v[82:97], v[200:203], v[102:105], v[82:97]
	ds_read_b128 v[200:203], v252 offset:6688
	v_exp_f32_e32 v61, v61
	v_exp_f32_e32 v62, v62
	v_exp_f32_e32 v63, v63
	s_waitcnt lgkmcnt(5)
	v_mfma_f32_32x32x16_bf16 v[82:97], v[216:219], v[106:109], v[82:97]
	ds_read_b128 v[216:219], v252 offset:6720
	v_exp_f32_e32 v64, v64
	v_exp_f32_e32 v65, v65
	v_exp_f32_e32 v34, v34
	s_waitcnt lgkmcnt(5)
	v_mfma_f32_32x32x16_bf16 v[82:97], v[230:233], v[110:113], v[82:97]
	ds_read_b128 v[230:233], v252 offset:6752
	v_exp_f32_e32 v35, v35
	v_cvt_pk_bf16_f32 v168, v50, v51
	v_exp_f32_e32 v36, v36
	v_exp_f32_e32 v37, v37
	s_waitcnt lgkmcnt(5)
	v_mfma_f32_32x32x16_bf16 v[82:97], v[234:237], v[114:117], v[82:97]
	ds_read_b128 v[234:237], v252 offset:6784
	v_cvt_pk_bf16_f32 v169, v52, v53
	v_exp_f32_e32 v38, v38
	v_exp_f32_e32 v39, v39
	v_cvt_pk_bf16_f32 v170, v54, v55
	s_waitcnt lgkmcnt(5)
	v_mfma_f32_32x32x16_bf16 v[82:97], v[244:247], v[118:121], v[82:97]
	ds_read_b128 v[244:247], v252 offset:6816
	v_exp_f32_e32 v40, v40
	v_exp_f32_e32 v41, v41
	v_cvt_pk_bf16_f32 v171, v56, v57
	v_exp_f32_e32 v42, v42
	s_waitcnt lgkmcnt(5)
	v_mfma_f32_32x32x16_bf16 v[66:81], v[196:199], v[98:101], v[66:81]
	ds_read_b128 v[196:199], v243 offset:53248
	v_exp_f32_e32 v43, v43
	v_cvt_pk_bf16_f32 v180, v58, v59
	v_exp_f32_e32 v44, v44
	v_exp_f32_e32 v45, v45
	s_waitcnt lgkmcnt(5)
	v_mfma_f32_32x32x16_bf16 v[66:81], v[200:203], v[102:105], v[66:81]
	ds_read_b128 v[200:203], v243 offset:57856
	v_cvt_pk_bf16_f32 v181, v60, v61
	v_exp_f32_e32 v46, v46
	v_exp_f32_e32 v47, v47
	v_cvt_pk_bf16_f32 v182, v62, v63
	s_waitcnt lgkmcnt(5)
	v_mfma_f32_32x32x16_bf16 v[66:81], v[216:219], v[106:109], v[66:81]
	ds_read_b128 v[216:219], v243 offset:53280
	v_exp_f32_e32 v48, v48
	v_exp_f32_e32 v49, v49
	v_cvt_pk_bf16_f32 v183, v64, v65
	v_add_f32_e32 v172, v50, v54
	s_waitcnt lgkmcnt(5)
	v_mfma_f32_32x32x16_bf16 v[66:81], v[230:233], v[110:113], v[66:81]
	ds_read_b128 v[230:233], v243 offset:57888
	v_add_f32_e32 v173, v51, v55
	v_add_f32_e32 v176, v52, v56
	v_add_f32_e32 v179, v53, v57
	v_add_f32_e32 v172, v58, v172
	v_add_f32_e32 v173, v59, v173
	v_add_f32_e32 v176, v60, v176
	s_waitcnt lgkmcnt(5)
	v_mfma_f32_32x32x16_bf16 v[66:81], v[234:237], v[114:117], v[66:81]
	ds_read_b128 v[234:237], v243 offset:53312
	v_add_f32_e32 v179, v61, v179
	v_add_f32_e32 v172, v62, v172
	v_add_f32_e32 v173, v63, v173
	v_add_f32_e32 v176, v64, v176
	v_add_f32_e32 v179, v65, v179
	v_cvt_pk_bf16_f32 v184, v34, v35
	s_waitcnt lgkmcnt(5)
	v_mfma_f32_32x32x16_bf16 v[66:81], v[244:247], v[118:121], v[66:81]
	ds_read_b128 v[244:247], v243 offset:57920
	v_cvt_pk_bf16_f32 v185, v36, v37
	v_cvt_pk_bf16_f32 v186, v38, v39
	v_cvt_pk_bf16_f32 v187, v40, v41
	v_cvt_pk_bf16_f32 v188, v42, v43
	v_cvt_pk_bf16_f32 v189, v44, v45
	v_cvt_pk_bf16_f32 v190, v46, v47
	s_waitcnt lgkmcnt(5)
	v_mfma_f32_32x32x16_bf16 v[18:33], v[196:199], v[168:171], v[18:33]
	ds_read_b128 v[196:199], v243 offset:53344
	v_cvt_pk_bf16_f32 v191, v48, v49
	v_add_f32_e32 v172, v34, v172
	v_add_f32_e32 v173, v35, v173
	v_add_f32_e32 v176, v36, v176
	v_add_f32_e32 v179, v37, v179
	v_add_f32_e32 v172, v38, v172
	s_waitcnt lgkmcnt(5)
	v_mfma_f32_32x32x16_bf16 v[2:17], v[200:203], v[168:171], v[2:17]
	ds_read_b128 v[200:203], v243 offset:57952
	v_add_f32_e32 v173, v39, v173
	v_add_f32_e32 v176, v40, v176
	v_add_f32_e32 v179, v41, v179
	v_add_f32_e32 v172, v42, v172
	v_add_f32_e32 v173, v43, v173
	v_add_f32_e32 v176, v44, v176
	s_waitcnt lgkmcnt(5)
	v_mfma_f32_32x32x16_bf16 v[18:33], v[216:219], v[180:183], v[18:33]
	v_add_f32_e32 v179, v45, v179
	v_add_f32_e32 v172, v46, v172
	v_add_f32_e32 v173, v47, v173
	v_add_f32_e32 v176, v48, v176
	v_add_f32_e32 v179, v49, v179
	v_add_f32_e32 v172, v172, v173
	s_waitcnt lgkmcnt(4)
	v_mfma_f32_32x32x16_bf16 v[2:17], v[230:233], v[180:183], v[2:17]
	v_add_f32_e32 v176, v176, v179
	s_waitcnt lgkmcnt(3)
	v_mfma_f32_32x32x16_bf16 v[18:33], v[234:237], v[184:187], v[18:33]
	s_waitcnt lgkmcnt(2)
	v_mfma_f32_32x32x16_bf16 v[2:17], v[244:247], v[184:187], v[2:17]
	s_waitcnt lgkmcnt(1)
	v_mfma_f32_32x32x16_bf16 v[18:33], v[196:199], v[188:191], v[18:33]
	s_waitcnt lgkmcnt(0)
	v_mfma_f32_32x32x16_bf16 v[2:17], v[200:203], v[188:191], v[2:17]
	v_add_f32_e32 v0, v172, v176
	v_add_f32_e32 v161, v161, v0
	s_setprio 0
	s_cmp_ge_u32 s25, s17
	s_cbranch_scc1 .LBB0_284
	v_cndmask_b32_e64 v0, 0, 1, s[66:67]
	v_cmp_ne_u32_e64 s[50:51], 1, v0
	s_andn2_b64 vcc, exec, s[66:67]
	s_cbranch_vccz .LBB0_285
	s_and_b64 vcc, exec, s[48:49]
	s_cbranch_vccz .LBB0_290
